# stack + combine phase: the four partial loads issued together with the lse loads (independent of the weights) instead of four load-wait-use rounds per token
# speedup vs baseline: 1.0148x; 1.0071x over previous
.LBB0_465:
	v_lshl_add_u64 v[6:7], s[20:21], 0, v[4:5]
	v_add_co_u32_e32 v8, vcc, 0x1f100000, v6
	v_mov_b32_e32 v16, 0
	s_nop 0
	v_addc_co_u32_e32 v9, vcc, 0, v7, vcc
	v_add_co_u32_e32 v10, vcc, 0x1f300000, v6
	v_mov_b32_e32 v17, v16
	s_nop 0
	v_addc_co_u32_e32 v11, vcc, 0, v7, vcc
	v_add_co_u32_e32 v12, vcc, 0x1f500000, v6
	v_mov_b64_e32 v[18:19], v[16:17]
	s_nop 0
	v_addc_co_u32_e32 v13, vcc, 0, v7, vcc
	v_add_co_u32_e32 v6, vcc, 0x1f700000, v6
	v_mov_b64_e32 v[20:21], v[16:17]
	s_nop 0
	v_addc_co_u32_e32 v7, vcc, 0, v7, vcc
	global_load_dword v14, v[8:9], off
	global_load_dword v27, v[10:11], off
	global_load_dword v26, v[12:13], off
	global_load_dword v24, v[6:7], off
	v_lshl_add_u64 v[62:63], s[20:21], 0, v[2:3]
	v_add_co_u32_e32 v46, vcc, 0x13100000, v62
	s_nop 1
	v_addc_co_u32_e32 v47, vcc, 0, v63, vcc
	global_load_dwordx4 v[46:49], v[46:47], off
	v_add_co_u32_e32 v50, vcc, 0x15100000, v62
	s_nop 1
	v_addc_co_u32_e32 v51, vcc, 0, v63, vcc
	global_load_dwordx4 v[50:53], v[50:51], off
	v_add_co_u32_e32 v54, vcc, 0x17100000, v62
	s_nop 1
	v_addc_co_u32_e32 v55, vcc, 0, v63, vcc
	global_load_dwordx4 v[54:57], v[54:55], off
	v_lshl_add_u64 v[58:59], s[18:19], 0, v[2:3]
	global_load_dwordx4 v[58:61], v[58:59], off
	v_mov_b64_e32 v[6:7], v[16:17]
	v_mov_b64_e32 v[8:9], v[16:17]
	v_mov_b64_e32 v[10:11], v[16:17]
	v_mov_b64_e32 v[12:13], v[16:17]
	v_mov_b64_e32 v[22:23], v[16:17]
	s_waitcnt vmcnt(6)
	v_max3_f32 v15, v14, s10, v27
	s_waitcnt vmcnt(4)
	v_max3_f32 v25, v15, v26, v24
	v_sub_f32_e32 v14, v14, v25
	v_exp_f32_e32 v28, v14
	v_mov_b64_e32 v[14:15], v[16:17]
	v_cmp_lt_f32_e32 vcc, 0, v28
	s_and_saveexec_b64 s[8:9], vcc
	s_cbranch_execz .LBB0_467
	v_mul_f32_e32 v16, 0x3d800000, v28
	s_waitcnt vmcnt(3)
	v_cvt_pk_f32_fp8_e32 v[10:11], v46
	v_cvt_pk_f32_fp8_sdwa v[12:13], v46 src0_sel:WORD_1
	v_cvt_pk_f32_fp8_e32 v[14:15], v47
	v_cvt_pk_f32_fp8_sdwa v[6:7], v47 src0_sel:WORD_1
	v_cvt_pk_f32_fp8_e32 v[30:31], v48
	v_cvt_pk_f32_fp8_sdwa v[32:33], v48 src0_sel:WORD_1
	v_cvt_pk_f32_fp8_e32 v[34:35], v49
	v_cvt_pk_f32_fp8_sdwa v[36:37], v49 src0_sel:WORD_1
	v_pk_fma_f32 v[22:23], v[16:17], v[10:11], 0 op_sel_hi:[0,1,0]
	v_pk_fma_f32 v[20:21], v[16:17], v[12:13], 0 op_sel_hi:[0,1,0]
	v_pk_fma_f32 v[18:19], v[16:17], v[14:15], 0 op_sel_hi:[0,1,0]
	v_pk_fma_f32 v[14:15], v[16:17], v[6:7], 0 op_sel_hi:[0,1,0]
	v_pk_fma_f32 v[12:13], v[16:17], v[30:31], 0 op_sel_hi:[0,1,0]
	v_pk_fma_f32 v[10:11], v[16:17], v[32:33], 0 op_sel_hi:[0,1,0]
	v_pk_fma_f32 v[8:9], v[16:17], v[34:35], 0 op_sel_hi:[0,1,0]
	v_pk_fma_f32 v[6:7], v[16:17], v[36:37], 0 op_sel_hi:[0,1,0]
	v_mov_b32_e32 v16, v28
.LBB0_467:
	s_or_b64 exec, exec, s[8:9]
	v_sub_f32_e32 v17, v27, v25
	v_exp_f32_e32 v17, v17
	s_nop 0
	v_cmp_lt_f32_e32 vcc, 0, v17
	s_and_saveexec_b64 s[8:9], vcc
	s_cbranch_execz .LBB0_469
	v_mul_f32_e32 v32, 0x3d800000, v17
	v_add_f32_e32 v16, v16, v17
	s_waitcnt vmcnt(2)
	v_cvt_pk_f32_fp8_e32 v[34:35], v50
	v_cvt_pk_f32_fp8_sdwa v[36:37], v50 src0_sel:WORD_1
	v_cvt_pk_f32_fp8_e32 v[38:39], v51
	v_cvt_pk_f32_fp8_sdwa v[28:29], v51 src0_sel:WORD_1
	v_cvt_pk_f32_fp8_e32 v[40:41], v52
	v_cvt_pk_f32_fp8_sdwa v[42:43], v52 src0_sel:WORD_1
	v_cvt_pk_f32_fp8_e32 v[44:45], v53
	v_cvt_pk_f32_fp8_sdwa v[30:31], v53 src0_sel:WORD_1
	v_pk_fma_f32 v[22:23], v[32:33], v[34:35], v[22:23] op_sel_hi:[0,1,1]
	v_pk_fma_f32 v[20:21], v[32:33], v[36:37], v[20:21] op_sel_hi:[0,1,1]
	v_pk_fma_f32 v[18:19], v[32:33], v[38:39], v[18:19] op_sel_hi:[0,1,1]
	v_pk_fma_f32 v[14:15], v[32:33], v[28:29], v[14:15] op_sel_hi:[0,1,1]
	v_pk_fma_f32 v[12:13], v[32:33], v[40:41], v[12:13] op_sel_hi:[0,1,1]
	v_pk_fma_f32 v[10:11], v[32:33], v[42:43], v[10:11] op_sel_hi:[0,1,1]
	v_pk_fma_f32 v[8:9], v[32:33], v[44:45], v[8:9] op_sel_hi:[0,1,1]
	v_pk_fma_f32 v[6:7], v[32:33], v[30:31], v[6:7] op_sel_hi:[0,1,1]
.LBB0_469:
	s_or_b64 exec, exec, s[8:9]
	v_sub_f32_e32 v17, v26, v25
	v_exp_f32_e32 v17, v17
	s_nop 0
	v_cmp_lt_f32_e32 vcc, 0, v17
	s_and_saveexec_b64 s[8:9], vcc
	s_cbranch_execz .LBB0_471
	v_mul_f32_e32 v30, 0x3d800000, v17
	v_add_f32_e32 v16, v16, v17
	s_waitcnt vmcnt(1)
	v_cvt_pk_f32_fp8_e32 v[32:33], v54
	v_cvt_pk_f32_fp8_sdwa v[34:35], v54 src0_sel:WORD_1
	v_cvt_pk_f32_fp8_e32 v[36:37], v55
	v_cvt_pk_f32_fp8_sdwa v[26:27], v55 src0_sel:WORD_1
	v_cvt_pk_f32_fp8_e32 v[38:39], v56
	v_cvt_pk_f32_fp8_sdwa v[40:41], v56 src0_sel:WORD_1
	v_cvt_pk_f32_fp8_e32 v[42:43], v57
	v_cvt_pk_f32_fp8_sdwa v[28:29], v57 src0_sel:WORD_1
	v_pk_fma_f32 v[22:23], v[30:31], v[32:33], v[22:23] op_sel_hi:[0,1,1]
	v_pk_fma_f32 v[20:21], v[30:31], v[34:35], v[20:21] op_sel_hi:[0,1,1]
	v_pk_fma_f32 v[18:19], v[30:31], v[36:37], v[18:19] op_sel_hi:[0,1,1]
	v_pk_fma_f32 v[14:15], v[30:31], v[26:27], v[14:15] op_sel_hi:[0,1,1]
	v_pk_fma_f32 v[12:13], v[30:31], v[38:39], v[12:13] op_sel_hi:[0,1,1]
	v_pk_fma_f32 v[10:11], v[30:31], v[40:41], v[10:11] op_sel_hi:[0,1,1]
	v_pk_fma_f32 v[8:9], v[30:31], v[42:43], v[8:9] op_sel_hi:[0,1,1]
	v_pk_fma_f32 v[6:7], v[30:31], v[28:29], v[6:7] op_sel_hi:[0,1,1]
.LBB0_471:
	s_or_b64 exec, exec, s[8:9]
	v_sub_f32_e32 v17, v24, v25
	v_exp_f32_e32 v17, v17
	s_nop 0
	v_cmp_lt_f32_e32 vcc, 0, v17
	s_and_saveexec_b64 s[8:9], vcc
	s_cbranch_execz .LBB0_464
	v_mul_f32_e32 v28, 0x3d800000, v17
	v_add_f32_e32 v16, v16, v17
	s_waitcnt vmcnt(0)
	v_cvt_pk_f32_fp8_e32 v[30:31], v58
	v_cvt_pk_f32_fp8_sdwa v[32:33], v58 src0_sel:WORD_1
	v_cvt_pk_f32_fp8_e32 v[34:35], v59
	v_cvt_pk_f32_fp8_sdwa v[24:25], v59 src0_sel:WORD_1
	v_cvt_pk_f32_fp8_e32 v[36:37], v60
	v_cvt_pk_f32_fp8_sdwa v[38:39], v60 src0_sel:WORD_1
	v_cvt_pk_f32_fp8_e32 v[40:41], v61
	v_cvt_pk_f32_fp8_sdwa v[26:27], v61 src0_sel:WORD_1
	v_pk_fma_f32 v[22:23], v[28:29], v[30:31], v[22:23] op_sel_hi:[0,1,1]
	v_pk_fma_f32 v[20:21], v[28:29], v[32:33], v[20:21] op_sel_hi:[0,1,1]
	v_pk_fma_f32 v[18:19], v[28:29], v[34:35], v[18:19] op_sel_hi:[0,1,1]
	v_pk_fma_f32 v[14:15], v[28:29], v[24:25], v[14:15] op_sel_hi:[0,1,1]
	v_pk_fma_f32 v[12:13], v[28:29], v[36:37], v[12:13] op_sel_hi:[0,1,1]
	v_pk_fma_f32 v[10:11], v[28:29], v[38:39], v[10:11] op_sel_hi:[0,1,1]
	v_pk_fma_f32 v[8:9], v[28:29], v[40:41], v[8:9] op_sel_hi:[0,1,1]
	v_pk_fma_f32 v[6:7], v[28:29], v[26:27], v[6:7] op_sel_hi:[0,1,1]
	s_branch .LBB0_464
